# baseline (speedup 1.0000x reference)
; #define SCHEDB() __builtin_amdgcn_sched_barrier(0)
; template <bool FIX>
; DEVI void attn_item(const bfr* __restrict__ Qb, const bfr* __restrict__ Kh, const bfr* __restrict__ Vh, bfr* __restrict__ Ob, int seq, char* lds, float negBC) {
;     ...
;   for (int j = 0; j < NT; ++j) {
;     const int buf = j & 1;
;     SCHEDB(); qkt(pA0, pA1, K_lds + buf * SHM_K, qr, r32, hi);
;     if (j + 1 < NT) { SWRITE(buf ^ 1, 0); if (j + 2 < NT) SLOAD(0, (j + 2) * KVBLK); }
.LBB0_121:
	s_and_b32 s2, s1, 1
	s_mul_i32 s4, s2, 0x6400
	v_add3_u32 v191, s4, v189, v166
	s_xor_b32 s4, s4, 0x6400
	s_cmp_eq_u32 s100, 0x4000
	s_cselect_b32 s101, 0x15000, 0
	s_cmp_eq_u32 s100, 0
	s_cselect_b32 s101, 0x4000, s101
	v_add_u32_e32 v194, s101, v187
	ds_read_b128 v[196:199], v191 offset:32768
	ds_read_b128 v[200:203], v191 offset:32800
	ds_read_b128 v[204:207], v191 offset:32832
	ds_read_b128 v[224:227], v191 offset:32864
	ds_read_b128 v[228:231], v191 offset:32896
	ds_read_b128 v[232:235], v191 offset:32928
	ds_read_b128 v[236:239], v191 offset:32960
	ds_read_b128 v[240:243], v191 offset:32992
	v_cvt_pk_bf16_f32 v208, v80, v81
	v_cvt_pk_bf16_f32 v209, v82, v83
	v_cvt_pk_bf16_f32 v210, v84, v85
	v_cvt_pk_bf16_f32 v211, v86, v87
	v_cvt_pk_bf16_f32 v212, v88, v89
	v_cvt_pk_bf16_f32 v213, v90, v91
	v_cvt_pk_bf16_f32 v214, v92, v93
	v_cvt_pk_bf16_f32 v215, v94, v95
	v_cvt_pk_bf16_f32 v216, v64, v65
	v_cvt_pk_bf16_f32 v217, v66, v67
	v_cvt_pk_bf16_f32 v218, v68, v69
	v_cvt_pk_bf16_f32 v219, v70, v71
	v_cvt_pk_bf16_f32 v220, v72, v73
	v_cvt_pk_bf16_f32 v221, v74, v75
	v_cvt_pk_bf16_f32 v222, v76, v77
	v_cvt_pk_bf16_f32 v223, v78, v79
	s_nop 1
	s_waitcnt lgkmcnt(7)
	v_mfma_f32_32x32x16_bf16 v[80:95], v[196:199], v[140:143], 0
	ds_read_b128 v[244:247], v191 offset:33024
	s_waitcnt lgkmcnt(7)
	v_mfma_f32_32x32x16_bf16 v[80:95], v[200:203], v[136:139], v[80:95]
	ds_read_b128 v[248:251], v191 offset:33056
	v_add_u32_e32 v181, s100, v185
	s_waitcnt vmcnt(0)
	ds_write_b128 v181, v[144:147]
	s_waitcnt lgkmcnt(8)
	v_mfma_f32_32x32x16_bf16 v[80:95], v[204:207], v[132:135], v[80:95]
	ds_read_b128 v[196:199], v191 offset:33088
	ds_write_b128 v181, v[148:151] offset:8192
	s_waitcnt lgkmcnt(9)
	v_mfma_f32_32x32x16_bf16 v[80:95], v[224:227], v[128:131], v[80:95]
	ds_read_b128 v[200:203], v191 offset:33120
	v_add_u32_e32 v181, s4, v172
	ds_write_b128 v181, v[152:155] offset:32768
	s_waitcnt lgkmcnt(10)
	v_mfma_f32_32x32x16_bf16 v[80:95], v[228:231], v[124:127], v[80:95]
	ds_read_b128 v[204:207], v191 offset:45568
	ds_write_b128 v181, v[156:159] offset:45568
	s_waitcnt lgkmcnt(11)
	v_mfma_f32_32x32x16_bf16 v[80:95], v[232:235], v[120:123], v[80:95]
	ds_read_b128 v[224:227], v191 offset:45600
	v_add_u32_e32 v181, s4, v188
	ds_write_b128 v181, v[160:163] offset:32768
	s_waitcnt lgkmcnt(12)
	v_mfma_f32_32x32x16_bf16 v[80:95], v[236:239], v[116:119], v[80:95]
	ds_read_b128 v[228:231], v191 offset:45632
	s_cmp_ge_u32 s1, s6
	s_cbranch_scc1 .Lfa_skipload
	global_load_dwordx4 v[144:147], v174, s[82:83]
	global_load_dwordx4 v[148:151], v175, s[82:83]
	global_load_dwordx4 v[152:155], v176, s[34:35]
	global_load_dwordx4 v[156:159], v177, s[34:35]
	global_load_dwordx4 v[160:163], v178, s[34:35] offset:256
	s_add_u32 s34, s34, 0x60000
	s_addc_u32 s35, s35, 0
	s_add_u32 s82, s82, 0x40000
	s_addc_u32 s83, s83, 0
; DEVI void finishSM(f32x16& p0, f32x16& p1, float alpha, float& l_reg, bf16x8& pa0, bf16x8& pa1, bf16x8& pa2, bf16x8& pa3) {
; #pragma unroll
;   for (int r = 0; r < 16; ++r) p1[r] = __builtin_amdgcn_exp2f(p1[r]);
;   float ps = 0;
; #pragma unroll
;   for (int r = 0; r < 16; ++r) ps += p0[r];
; #pragma unroll
;   for (int r = 0; r < 16; ++r) ps += p1[r];
;   { auto rr = __builtin_amdgcn_permlane32_swap(__float_as_uint(ps), __float_as_uint(ps), false, false);
;     ps = __uint_as_float(rr[0]) + __uint_as_float(rr[1]); }
;   l_reg = l_reg * alpha + ps;
;     ...
;   PK4(p0, 0, pa0); PK4(p0, 8, pa1); PK4(p1, 0, pa2); PK4(p1, 8, pa3);
;     ...
; }
; DEVI void qkt(f32x16& p0, f32x16& p1, const char* Ks, const bf16x8* qr, int r32, int hi) {
;   p0 = f32x16{}; p1 = f32x16{};
; #pragma unroll
;   for (int d0 = 0; d0 < 12; ++d0) { int cb = (d0 * 16 + hi * 8) * 2;
;     bf16x8 b0 = *reinterpret_cast<const bf16x8*>(Ks + KSWZ(r32, cb));
;     bf16x8 b1 = *reinterpret_cast<const bf16x8*>(Ks + KSWZ(32 + r32, cb));
;     p0 = __builtin_amdgcn_mfma_f32_32x32x16_bf16(b0, qr[d0], p0, 0, 0, 0);
;     p1 = __builtin_amdgcn_mfma_f32_32x32x16_bf16(b1, qr[d0], p1, 0, 0, 0); }
; }
; DEVI int v_st(int k, int c) { const int kk = (k & ~0xC) | ((k & 4) << 1) | ((k & 8) >> 1); return ((kk >> 3) * 4 + (c >> 5)) * 512 + ((kk & 7) * 32 + (c & 31)) * 2; }
; DEVI int v_rd_base(int lane) { return ((lane & 3) << 3) | (((lane >> 2) & 3) << 6) | (((lane >> 4) & 1) << 5) | (((lane >> 5) & 1) << 8); }
; template <int OFF> DEVI s16x4 tr_read(int vb) {
;   s16x4 r; asm volatile("ds_read_b64_tr_b16 %0, %1 offset:%2" : "=&v"(r) : "v"(vb), "i"(OFF) : "memory"); return r;
; }
; template <int D0> DEVI void pv_one(f32x16& od, int vb, bf16x8 pa0, bf16x8 pa1, bf16x8 pa2, bf16x8 pa3) {
;   const s16x4 l0 = tr_read<v_rd_off(D0, 0, 0)>(vb), h0 = tr_read<v_rd_off(D0, 0, 1)>(vb), l1 = tr_read<v_rd_off(D0, 1, 0)>(vb), h1 = tr_read<v_rd_off(D0, 1, 1)>(vb);
;   const s16x4 l2 = tr_read<v_rd_off(D0, 2, 0)>(vb), h2 = tr_read<v_rd_off(D0, 2, 1)>(vb), l3 = tr_read<v_rd_off(D0, 3, 0)>(vb), h3 = tr_read<v_rd_off(D0, 3, 1)>(vb);
;   asm volatile("s_waitcnt lgkmcnt(0)" ::: "memory"); SCHEDB();
;     ...
;   od = __builtin_amdgcn_mfma_f32_32x32x16_bf16(pa0, PK(l0, h0), od, 0, 0, 0);
;   od = __builtin_amdgcn_mfma_f32_32x32x16_bf16(pa1, PK(l1, h1), od, 0, 0, 0);
;   od = __builtin_amdgcn_mfma_f32_32x32x16_bf16(pa2, PK(l2, h2), od, 0, 0, 0);
.Lfa_skipload:
	s_waitcnt lgkmcnt(12)
	v_mfma_f32_32x32x16_bf16 v[80:95], v[240:243], v[112:115], v[80:95]
	ds_read_b128 v[232:235], v191 offset:45664
	s_waitcnt lgkmcnt(12)
	v_mfma_f32_32x32x16_bf16 v[80:95], v[244:247], v[108:111], v[80:95]
	ds_read_b128 v[236:239], v191 offset:45696
	s_waitcnt lgkmcnt(12)
	v_mfma_f32_32x32x16_bf16 v[80:95], v[248:251], v[104:107], v[80:95]
	ds_read_b128 v[240:243], v191 offset:45728
	s_waitcnt lgkmcnt(11)
	v_mfma_f32_32x32x16_bf16 v[80:95], v[196:199], v[100:103], v[80:95]
	ds_read_b128 v[244:247], v191 offset:45760
	s_waitcnt lgkmcnt(10)
	v_mfma_f32_32x32x16_bf16 v[80:95], v[200:203], v[96:99], v[80:95]
	ds_read_b128 v[248:251], v191 offset:45792
	s_waitcnt lgkmcnt(9)
	v_mfma_f32_32x32x16_bf16 v[64:79], v[204:207], v[140:143], 0
	ds_read_b128 v[196:199], v191 offset:45824
	s_waitcnt lgkmcnt(8)
	v_mfma_f32_32x32x16_bf16 v[64:79], v[224:227], v[136:139], v[64:79]
	ds_read_b128 v[200:203], v191 offset:45856
	s_waitcnt lgkmcnt(7)
	v_mfma_f32_32x32x16_bf16 v[64:79], v[228:231], v[132:135], v[64:79]
	ds_read_b128 v[204:207], v191 offset:45888
	s_waitcnt lgkmcnt(7)
	v_mfma_f32_32x32x16_bf16 v[64:79], v[232:235], v[128:131], v[64:79]
	ds_read_b128 v[224:227], v191 offset:45920
	v_exp_f32_e32 v80, v80
	v_exp_f32_e32 v81, v81
	s_waitcnt lgkmcnt(7)
	v_mfma_f32_32x32x16_bf16 v[64:79], v[236:239], v[124:127], v[64:79]
	ds_read_b64_tr_b16 v[228:229], v194 offset:0
	ds_read_b64_tr_b16 v[230:231], v194 offset:2048
	v_exp_f32_e32 v82, v82
	v_add_f32_e32 v192, v80, v81
	v_exp_f32_e32 v83, v83
	v_add_f32_e32 v192, v82, v192
	v_add_f32_e32 v192, v83, v192
	s_waitcnt lgkmcnt(8)
	v_mfma_f32_32x32x16_bf16 v[64:79], v[240:243], v[120:123], v[64:79]
	ds_read_b64_tr_b16 v[232:233], v194 offset:4096
	ds_read_b64_tr_b16 v[234:235], v194 offset:6144
	v_exp_f32_e32 v84, v84
	v_exp_f32_e32 v85, v85
	v_add_f32_e32 v192, v84, v192
	v_add_f32_e32 v192, v85, v192
	s_waitcnt lgkmcnt(9)
	v_mfma_f32_32x32x16_bf16 v[64:79], v[244:247], v[116:119], v[64:79]
	ds_read_b64_tr_b16 v[236:237], v194 offset:8192
	ds_read_b64_tr_b16 v[238:239], v194 offset:10240
	v_exp_f32_e32 v86, v86
	v_exp_f32_e32 v87, v87
	v_add_f32_e32 v192, v86, v192
	v_add_f32_e32 v192, v87, v192
	s_waitcnt lgkmcnt(10)
	v_mfma_f32_32x32x16_bf16 v[64:79], v[248:251], v[112:115], v[64:79]
	ds_read_b64_tr_b16 v[240:241], v194 offset:12288
	ds_read_b64_tr_b16 v[242:243], v194 offset:14336
	v_exp_f32_e32 v88, v88
	v_exp_f32_e32 v89, v89
	v_add_f32_e32 v192, v88, v192
	v_add_f32_e32 v192, v89, v192
	s_waitcnt lgkmcnt(11)
	v_mfma_f32_32x32x16_bf16 v[64:79], v[196:199], v[108:111], v[64:79]
	ds_read_b64_tr_b16 v[244:245], v194 offset:512
	ds_read_b64_tr_b16 v[246:247], v194 offset:2560
	v_exp_f32_e32 v90, v90
	v_exp_f32_e32 v91, v91
	v_add_f32_e32 v192, v90, v192
	v_add_f32_e32 v192, v91, v192
	s_waitcnt lgkmcnt(12)
	v_mfma_f32_32x32x16_bf16 v[64:79], v[200:203], v[104:107], v[64:79]
	ds_read_b64_tr_b16 v[248:249], v194 offset:4608
	ds_read_b64_tr_b16 v[250:251], v194 offset:6656
	v_exp_f32_e32 v92, v92
	v_exp_f32_e32 v93, v93
	v_add_f32_e32 v192, v92, v192
	v_add_f32_e32 v192, v93, v192
	s_waitcnt lgkmcnt(13)
	v_mfma_f32_32x32x16_bf16 v[64:79], v[204:207], v[100:103], v[64:79]
	ds_read_b64_tr_b16 v[196:197], v194 offset:8704
	ds_read_b64_tr_b16 v[198:199], v194 offset:10752
	v_exp_f32_e32 v94, v94
	v_exp_f32_e32 v95, v95
	v_add_f32_e32 v192, v94, v192
	v_add_f32_e32 v192, v95, v192
	s_waitcnt lgkmcnt(14)
	v_mfma_f32_32x32x16_bf16 v[64:79], v[224:227], v[96:99], v[64:79]
	s_cmp_eq_u32 s1, 0
	s_cbranch_scc1 .Lfa_first
	s_waitcnt lgkmcnt(12)
	v_mfma_f32_32x32x16_bf16 v[0:15], v[208:211], v[228:231], v[0:15]
	ds_read_b64_tr_b16 v[200:201], v194 offset:12800
	ds_read_b64_tr_b16 v[202:203], v194 offset:14848
	s_waitcnt lgkmcnt(12)
	v_mfma_f32_32x32x16_bf16 v[0:15], v[212:215], v[232:235], v[0:15]
	ds_read_b64_tr_b16 v[204:205], v194 offset:1024
	ds_read_b64_tr_b16 v[206:207], v194 offset:3072
	s_waitcnt lgkmcnt(12)
	v_mfma_f32_32x32x16_bf16 v[0:15], v[216:219], v[236:239], v[0:15]
	ds_read_b64_tr_b16 v[224:225], v194 offset:5120
	ds_read_b64_tr_b16 v[226:227], v194 offset:7168
	s_waitcnt lgkmcnt(12)
	v_mfma_f32_32x32x16_bf16 v[0:15], v[220:223], v[240:243], v[0:15]
	ds_read_b64_tr_b16 v[228:229], v194 offset:9216
	ds_read_b64_tr_b16 v[230:231], v194 offset:11264
	v_exp_f32_e32 v64, v64
	v_exp_f32_e32 v65, v65
	v_add_f32_e32 v192, v64, v192
	v_add_f32_e32 v192, v65, v192
	s_waitcnt lgkmcnt(12)
	v_mfma_f32_32x32x16_bf16 v[16:31], v[208:211], v[244:247], v[16:31]
	ds_read_b64_tr_b16 v[232:233], v194 offset:13312
	ds_read_b64_tr_b16 v[234:235], v194 offset:15360
	v_exp_f32_e32 v66, v66
	v_exp_f32_e32 v67, v67
	v_add_f32_e32 v192, v66, v192
	v_add_f32_e32 v192, v67, v192
	s_waitcnt lgkmcnt(12)
	v_mfma_f32_32x32x16_bf16 v[16:31], v[212:215], v[248:251], v[16:31]
	ds_read_b64_tr_b16 v[236:237], v194 offset:1536
	ds_read_b64_tr_b16 v[238:239], v194 offset:3584
	v_exp_f32_e32 v68, v68
	v_exp_f32_e32 v69, v69
	v_add_f32_e32 v192, v68, v192
	v_add_f32_e32 v192, v69, v192
	s_waitcnt lgkmcnt(12)
	v_mfma_f32_32x32x16_bf16 v[16:31], v[216:219], v[196:199], v[16:31]
	ds_read_b64_tr_b16 v[240:241], v194 offset:5632
	ds_read_b64_tr_b16 v[242:243], v194 offset:7680
	v_exp_f32_e32 v70, v70
	v_exp_f32_e32 v71, v71
	v_add_f32_e32 v192, v70, v192
	v_add_f32_e32 v192, v71, v192
	s_waitcnt lgkmcnt(12)
	v_mfma_f32_32x32x16_bf16 v[16:31], v[220:223], v[200:203], v[16:31]
	ds_read_b64_tr_b16 v[244:245], v194 offset:9728
	ds_read_b64_tr_b16 v[246:247], v194 offset:11776
	v_exp_f32_e32 v72, v72
	v_exp_f32_e32 v73, v73
	v_add_f32_e32 v192, v72, v192
	v_add_f32_e32 v192, v73, v192
	s_waitcnt lgkmcnt(12)
	v_mfma_f32_32x32x16_bf16 v[32:47], v[208:211], v[204:207], v[32:47]
	ds_read_b64_tr_b16 v[248:249], v194 offset:13824
	ds_read_b64_tr_b16 v[250:251], v194 offset:15872
	v_exp_f32_e32 v74, v74
	v_exp_f32_e32 v75, v75
	v_add_f32_e32 v192, v74, v192
	v_add_f32_e32 v192, v75, v192
	s_waitcnt lgkmcnt(12)
	v_mfma_f32_32x32x16_bf16 v[32:47], v[212:215], v[224:227], v[32:47]
	v_exp_f32_e32 v76, v76
	v_exp_f32_e32 v77, v77
	v_add_f32_e32 v192, v76, v192
	v_add_f32_e32 v192, v77, v192
	s_waitcnt lgkmcnt(10)
	v_mfma_f32_32x32x16_bf16 v[32:47], v[216:219], v[228:231], v[32:47]
	v_exp_f32_e32 v78, v78
	v_exp_f32_e32 v79, v79
	v_add_f32_e32 v192, v78, v192
	v_add_f32_e32 v192, v79, v192
	s_waitcnt lgkmcnt(8)
	v_mfma_f32_32x32x16_bf16 v[32:47], v[220:223], v[232:235], v[32:47]
	v_mov_b32_e32 v193, v192
	s_waitcnt lgkmcnt(6)
	v_mfma_f32_32x32x16_bf16 v[48:63], v[208:211], v[236:239], v[48:63]
	v_permlane32_swap_b32_e32 v192, v193
	v_add_f32_e32 v192, v192, v193
	v_add_f32_e32 v173, v173, v192
	s_waitcnt lgkmcnt(4)
	v_mfma_f32_32x32x16_bf16 v[48:63], v[212:215], v[240:243], v[48:63]
	s_add_i32 s1, s1, 1
	s_waitcnt lgkmcnt(2)
	v_mfma_f32_32x32x16_bf16 v[48:63], v[216:219], v[244:247], v[48:63]
	s_waitcnt lgkmcnt(0)
	v_mfma_f32_32x32x16_bf16 v[48:63], v[220:223], v[248:251], v[48:63]
